# post2 token loop: drop two store-drain vmcnt(0) waits per token (data wait hoisted above the hasq branch)
# speedup vs baseline: 1.0016x; 1.0016x over previous
.LBB0_536:
	s_movk_i32 s0, 0x3000
	v_cmp_gt_i32_e64 s[8:9], s0, v12
	s_movk_i32 s0, 0x600
	v_ashrrev_i32_e32 v13, 31, v12
	v_cndmask_b32_e64 v0, 0, v12, s[8:9]
	v_mad_i64_i32 v[14:15], s[0:1], v0, s0, v[2:3]
	global_load_ushort v16, v[14:15], off
	global_load_ushort v18, v[14:15], off offset:128
	global_load_ushort v17, v[14:15], off offset:256
	global_load_ushort v42, v[14:15], off offset:384
	global_load_ushort v44, v[14:15], off offset:512
	global_load_ushort v43, v[14:15], off offset:640
	global_load_ushort v39, v[14:15], off offset:768
	global_load_ushort v41, v[14:15], off offset:896
	global_load_ushort v40, v[14:15], off offset:1024
	global_load_ushort v36, v[14:15], off offset:1152
	global_load_ushort v38, v[14:15], off offset:1280
	global_load_ushort v37, v[14:15], off offset:1408
	v_lshlrev_b64 v[14:15], 11, v[12:13]
	v_lshl_add_u64 v[14:15], v[4:5], 0, v[14:15]
	global_load_ushort v33, v[14:15], off
	global_load_ushort v34, v[14:15], off offset:128
	global_load_ushort v20, v[14:15], off offset:512
	global_load_ushort v21, v[14:15], off offset:640
	global_load_ushort v31, v[14:15], off offset:1024
	global_load_ushort v32, v[14:15], off offset:1152
	global_load_ushort v29, v[14:15], off offset:1536
	global_load_ushort v30, v[14:15], off offset:1664
	v_lshlrev_b64 v[14:15], 7, v[12:13]
	v_lshl_add_u64 v[14:15], v[6:7], 0, v[14:15]
	global_load_ushort v35, v[14:15], off
	v_add_u32_e32 v0, 0xfffff000, v12
	s_movk_i32 s0, 0x2000
	v_cmp_gt_u32_e64 s[6:7], s0, v0
	v_mov_b32_e32 v13, 0
	v_mov_b32_e32 v0, 1.0
	s_and_saveexec_b64 s[72:73], s[6:7]
	s_cbranch_execz .LBB0_542
	v_bfe_u32 v0, v12, 6, 5
	v_and_b32_e32 v13, 63, v12
	v_cndmask_b32_e32 v0, v13, v0, vcc
	v_cvt_f32_ubyte0_e32 v0, v0
	v_mul_f32_e32 v13, v28, v0
	s_brev_b32 s0, 18
	v_cmp_ngt_f32_e64 s[10:11], s0, v13
	s_and_saveexec_b64 s[0:1], s[10:11]
	s_xor_b64 s[0:1], exec, s[0:1]
	s_cbranch_execz .LBB0_539
	v_lshrrev_b32_e32 v0, 23, v13
	v_add_u32_e32 v0, 0xffffff88, v0
	v_cmp_lt_u32_e64 s[10:11], 63, v0
	v_not_b32_e32 v14, 63
	v_not_b32_e32 v15, 31
	v_cndmask_b32_e64 v14, 0, v14, s[10:11]
	v_add_u32_e32 v0, v14, v0
	v_cmp_lt_u32_e64 s[12:13], 31, v0
	s_mov_b32 s4, 0xfe5163ab
	s_nop 0
	v_cndmask_b32_e64 v14, 0, v15, s[12:13]
	v_add_u32_e32 v0, v14, v0
	v_cmp_lt_u32_e64 s[14:15], 31, v0
	s_nop 1
	v_cndmask_b32_e64 v14, 0, v15, s[14:15]
	v_add_u32_e32 v19, v14, v0
	v_and_b32_e32 v0, 0x7fffff, v13
	v_or_b32_e32 v45, 0x800000, v0
	v_mad_u64_u32 v[14:15], s[16:17], v45, s4, 0
	v_mov_b32_e32 v0, v15
	s_mov_b32 s4, 0x3c439041
	v_mad_u64_u32 v[46:47], s[16:17], v45, s4, v[0:1]
	v_mov_b32_e32 v0, v47
	s_mov_b32 s4, 0xdb629599
	v_mad_u64_u32 v[48:49], s[16:17], v45, s4, v[0:1]
	v_mov_b32_e32 v0, v49
	s_mov_b32 s4, 0xf534ddc0
	v_mad_u64_u32 v[50:51], s[16:17], v45, s4, v[0:1]
	v_mov_b32_e32 v0, v51
	s_mov_b32 s4, 0xfc2757d1
	v_mad_u64_u32 v[52:53], s[16:17], v45, s4, v[0:1]
	v_mov_b32_e32 v0, v53
	s_mov_b32 s4, 0x4e441529
	v_mad_u64_u32 v[54:55], s[16:17], v45, s4, v[0:1]
	v_mov_b32_e32 v0, v55
	s_mov_b32 s4, 0xa2f9836e
	v_mad_u64_u32 v[56:57], s[16:17], v45, s4, v[0:1]
	v_cndmask_b32_e64 v15, v54, v50, s[10:11]
	v_cndmask_b32_e64 v0, v56, v52, s[10:11]
	v_cndmask_b32_e64 v47, v57, v54, s[10:11]
	v_cndmask_b32_e64 v45, v0, v15, s[12:13]
	v_cndmask_b32_e64 v0, v47, v0, s[12:13]
	v_cndmask_b32_e64 v47, v52, v48, s[10:11]
	v_cndmask_b32_e64 v15, v15, v47, s[12:13]
	v_cndmask_b32_e64 v0, v0, v45, s[14:15]
	v_cndmask_b32_e64 v45, v45, v15, s[14:15]
	v_sub_u32_e32 v49, 32, v19
	v_alignbit_b32 v51, v0, v45, v49
	v_cmp_eq_u32_e64 s[16:17], 0, v19
	v_cndmask_b32_e64 v14, v48, v14, s[10:11]
	s_mov_b32 s4, 0x3fc90fda
	v_cndmask_b32_e64 v19, v51, v0, s[16:17]
	v_cndmask_b32_e64 v0, v50, v46, s[10:11]
	v_cndmask_b32_e64 v46, v47, v0, s[12:13]
	v_cndmask_b32_e64 v15, v15, v46, s[14:15]
	v_alignbit_b32 v47, v45, v15, v49
	v_cndmask_b32_e64 v0, v0, v14, s[12:13]
	v_cndmask_b32_e64 v45, v47, v45, s[16:17]
	v_bfe_u32 v51, v19, 29, 1
	v_cndmask_b32_e64 v0, v46, v0, s[14:15]
	v_alignbit_b32 v47, v19, v45, 30
	v_sub_u32_e32 v52, 0, v51
	v_alignbit_b32 v14, v15, v0, v49
	v_xor_b32_e32 v47, v47, v52
	v_cndmask_b32_e64 v14, v14, v15, s[16:17]
	v_alignbit_b32 v15, v45, v14, 30
	v_ffbh_u32_e32 v45, v47
	v_min_u32_e32 v45, 32, v45
	v_alignbit_b32 v0, v14, v0, 30
	v_xor_b32_e32 v15, v15, v52
	v_sub_u32_e32 v46, 31, v45
	v_xor_b32_e32 v0, v0, v52
	v_alignbit_b32 v47, v47, v15, v46
	v_alignbit_b32 v0, v15, v0, v46
	v_alignbit_b32 v14, v47, v0, 9
	v_ffbh_u32_e32 v15, v14
	v_min_u32_e32 v15, 32, v15
	v_lshrrev_b32_e32 v50, 29, v19
	v_not_b32_e32 v46, v15
	v_alignbit_b32 v0, v14, v0, v46
	v_lshlrev_b32_e32 v14, 31, v50
	v_or_b32_e32 v46, 0x33000000, v14
	v_add_lshl_u32 v15, v15, v45, 23
	v_lshrrev_b32_e32 v0, 9, v0
	v_sub_u32_e32 v15, v46, v15
	v_or_b32_e32 v14, 0.5, v14
	v_lshlrev_b32_e32 v45, 23, v45
	v_or_b32_e32 v0, v15, v0
	v_lshrrev_b32_e32 v15, 9, v47
	v_sub_u32_e32 v14, v14, v45
	v_or_b32_e32 v14, v15, v14
	v_mul_f32_e32 v15, 0x3fc90fda, v14
	v_fma_f32 v45, v14, s4, -v15
	v_fmac_f32_e32 v45, 0x33a22168, v14
	v_fmac_f32_e32 v45, 0x3fc90fda, v0
	v_lshrrev_b32_e32 v14, 30, v19
	v_add_f32_e32 v0, v15, v45
	v_add_u32_e32 v14, v51, v14

.LBB0_542:
	s_or_b64 exec, exec, s[72:73]
	s_movk_i32 s0, 0x600
	v_mad_i64_i32 v[14:15], s[0:1], v12, s0, 0
	s_waitcnt vmcnt(0)
	s_and_saveexec_b64 s[10:11], s[8:9]
	s_cbranch_execz .LBB0_552
	v_lshlrev_b32_e32 v46, 16, v18
	v_lshlrev_b32_e32 v19, 16, v16
	v_lshlrev_b32_e32 v18, 16, v17
	v_pk_mul_f32 v[16:17], v[18:19], v[18:19]
	s_nop 0
	v_fma_f32 v17, v46, v46, v17
	v_add_f32_e32 v16, v16, v17
	v_mov_b32_e32 v17, v1
	s_nop 0
	v_add_f32_dpp v16, v16, v16 quad_perm:[1,0,3,2] row_mask:0xf bank_mask:0xf bound_ctrl:1
	s_nop 1
	v_add_f32_dpp v16, v16, v16 quad_perm:[2,3,0,1] row_mask:0xf bank_mask:0xf bound_ctrl:1
	s_nop 1
	v_add_f32_dpp v16, v16, v16 row_half_mirror row_mask:0xf bank_mask:0xf bound_ctrl:1
	s_nop 1
	v_add_f32_dpp v16, v16, v16 row_mirror row_mask:0xf bank_mask:0xf bound_ctrl:1
	s_nop 1
	v_mov_b32_dpp v17, v16 row_bcast:15 row_mask:0xa bank_mask:0xf
	v_add_f32_e32 v16, v16, v17
	v_mov_b32_e32 v17, v1
	s_nop 1
	v_mov_b32_dpp v17, v16 row_bcast:31 row_mask:0xc bank_mask:0xf
	v_add_f32_e32 v16, v16, v17
	s_nop 0
	v_readlane_b32 s0, v16, 63
	s_nop 1
	v_fma_f32 v16, s0, v227, v209
	s_mov_b32 s0, 0x800000
	v_mul_f32_e32 v17, 0x4b800000, v16
	v_cmp_gt_f32_e64 s[8:9], s0, v16
	s_nop 1
	v_cndmask_b32_e64 v16, v16, v17, s[8:9]
	v_rsq_f32_e32 v16, v16
	s_nop 0
	v_mul_f32_e32 v17, 0x45800000, v16
	v_cndmask_b32_e64 v47, v16, v17, s[8:9]
	v_mul_f32_e32 v16, v47, v18
	v_mul_f32_e32 v45, v25, v16
	s_and_saveexec_b64 s[0:1], s[6:7]
	s_cbranch_execz .LBB0_545
	v_and_b32_e32 v17, 64, v221
	v_xor_b32_e32 v16, 16, v221
	v_add_u32_e32 v17, 64, v17
	v_cmp_lt_i32_e64 s[8:9], v16, v17
	s_nop 1
	v_cndmask_b32_e64 v16, v221, v16, s[8:9]
	v_lshlrev_b32_e32 v16, 2, v16
	ds_bpermute_b32 v16, v16, v45
	s_waitcnt lgkmcnt(0)
	v_mul_f32_e32 v16, v13, v16
	v_cndmask_b32_e64 v16, v16, -v16, s[56:57]
	v_fmac_f32_e32 v16, v0, v45
	v_mov_b32_e32 v45, v16

.LBB0_552:
	s_or_b64 exec, exec, s[10:11]
	v_lshlrev_b32_e32 v17, 16, v35
	v_lshlrev_b32_e32 v16, 16, v33
	v_lshlrev_b32_e32 v34, 16, v34
	v_pk_mul_f32 v[18:19], v[16:17], v[16:17]
	v_mov_b32_e32 v33, v1
	v_fma_f32 v18, v34, v34, v18
	v_add_f32_e32 v18, v18, v19
	s_nop 1
	v_add_f32_dpp v18, v18, v18 quad_perm:[1,0,3,2] row_mask:0xf bank_mask:0xf bound_ctrl:1
	s_nop 1
	v_add_f32_dpp v18, v18, v18 quad_perm:[2,3,0,1] row_mask:0xf bank_mask:0xf bound_ctrl:1
	s_nop 1
	v_add_f32_dpp v18, v18, v18 row_half_mirror row_mask:0xf bank_mask:0xf bound_ctrl:1
	s_nop 1
	v_add_f32_dpp v18, v18, v18 row_mirror row_mask:0xf bank_mask:0xf bound_ctrl:1
	s_nop 1
	v_mov_b32_dpp v33, v18 row_bcast:15 row_mask:0xa bank_mask:0xf
	v_add_f32_e32 v18, v18, v33
	v_mov_b32_e32 v33, v1
	s_nop 1
	v_mov_b32_dpp v33, v18 row_bcast:31 row_mask:0xc bank_mask:0xf
	v_add_f32_e32 v18, v18, v33
	s_nop 0
	v_readlane_b32 s0, v18, 63
	s_nop 1
	v_fma_f32 v18, s0, v227, v209
	s_mov_b32 s0, 0x800000
	v_mul_f32_e32 v33, 0x4b800000, v18
	v_cmp_gt_f32_e64 s[8:9], s0, v18
	s_nop 1
	v_cndmask_b32_e64 v18, v18, v33, s[8:9]
	v_rsq_f32_e32 v18, v18
	s_nop 0
	v_mul_f32_e32 v33, 0x45800000, v18
	v_cndmask_b32_e64 v33, v18, v33, s[8:9]
	v_mul_f32_e32 v18, v33, v17
	v_mul_f32_e32 v18, v26, v18
	s_and_saveexec_b64 s[0:1], s[6:7]
	s_cbranch_execz .LBB0_554
	v_and_b32_e32 v36, 64, v221
	v_xor_b32_e32 v35, 16, v221
	v_add_u32_e32 v36, 64, v36
	v_cmp_lt_i32_e64 s[8:9], v35, v36
	s_nop 1
	v_cndmask_b32_e64 v35, v221, v35, s[8:9]
	v_lshlrev_b32_e32 v35, 2, v35
	ds_bpermute_b32 v35, v35, v18
	s_waitcnt lgkmcnt(0)
	v_mul_f32_e32 v35, v13, v35
	v_cndmask_b32_e64 v35, v35, -v35, s[56:57]
	v_fmac_f32_e32 v35, v0, v18
	v_mov_b32_e32 v18, v35
